# v28 + hand-written software-pipelined weight-conversion loop (two items in flight) with nt loads and write-through stores
# speedup vs baseline: 1.0054x; 1.0001x over previous
; #define LAS __attribute__((address_space(3)))
; __device__ __forceinline__ void tr_item(const float* W, int K, int N, const float* kscale, bf16* WT, int dst_row0, LAS float* scr, int k0, int n0, int lane) {
;     const int n4 = 4 * (lane & 7); const bool ok = (n0 + n4) < N;
; #pragma unroll
;     for (int i = 0; i < 8; ++i) { const int kk = 8 * i + (lane >> 3); f32x4 v = ok ? *(const f32x4*)(W + (size_t)(k0 + kk) * N + n0 + n4) : (f32x4){0.f, 0.f, 0.f, 0.f}; if (kscale) v = v * kscale[k0 + kk];
;         scr[kk * 33 + n4] = v[0]; scr[kk * 33 + n4 + 1] = v[1]; scr[kk * 33 + n4 + 2] = v[2]; scr[kk * 33 + n4 + 3] = v[3]; }
.Lwq_nm_0:
	v_add_u32_e32 v15, s30, v14
	v_add_u32_e32 v16, s30, v15
	v_add_u32_e32 v17, s30, v16
	v_add_u32_e32 v18, s30, v17
	v_add_u32_e32 v19, s30, v18
	v_add_u32_e32 v20, s30, v19
	v_add_u32_e32 v21, s30, v20
	global_load_dwordx4 v[80:83], v14, s[64:65] nt
	global_load_dwordx4 v[84:87], v15, s[64:65] nt
	global_load_dwordx4 v[88:91], v16, s[64:65] nt
	global_load_dwordx4 v[92:95], v17, s[64:65] nt
	global_load_dwordx4 v[96:99], v18, s[64:65] nt
	global_load_dwordx4 v[100:103], v19, s[64:65] nt
	global_load_dwordx4 v[104:107], v20, s[64:65] nt
	global_load_dwordx4 v[108:111], v21, s[64:65] nt
	global_load_dwordx4 v[112:115], v4, s[66:67]
	global_load_dwordx4 v[116:119], v4, s[66:67] offset:16

; __device__ __forceinline__ void tr_item(const float* W, int K, int N, const float* kscale, bf16* WT, int dst_row0, LAS float* scr, int k0, int n0, int lane) {
;     const int n4 = 4 * (lane & 7); const bool ok = (n0 + n4) < N;
; #pragma unroll
;     for (int i = 0; i < 8; ++i) { const int kk = 8 * i + (lane >> 3); f32x4 v = ok ? *(const f32x4*)(W + (size_t)(k0 + kk) * N + n0 + n4) : (f32x4){0.f, 0.f, 0.f, 0.f}; if (kscale) v = v * kscale[k0 + kk];
; __device__ __forceinline__ void prologue(const Args& a, LAS unsigned char* lds, int wave, int lane) {
;     ...
;     for (int it = gw; it < DEPTH * I_L; it += NGW) {
;         const int l = it / I_L; int r = it % I_L;
;         unsigned char* wl = ws + WS_W + (size_t)l * W_L;
;         if (r < 2 * I_W1) {
;             const bool second = r >= I_W1; if (second) r -= I_W1;
;             const float* W = a.in[second ? 14 : 2] + (size_t)l * D * NFF; const float* ks = a.in[second ? 13 : 1] + (size_t)l * D;
;             const int nblk = NFF / 32, kb = r / nblk, nb = r % nblk, n0 = 32 * nb;
;             const int dst = n0 < DFF ? (n0 / 128) * 256 + (n0 % 128) : ((n0 - DFF) / 128) * 256 + 128 + ((n0 - DFF) % 128);
;             tr_item(W, D, NFF, ks, (bf16*)(wl + (second ? W3_OFF : W1_OFF)), dst, scr, 64 * kb, n0, lane);
;             continue;
;         }
;         r -= 2 * I_W1;
;         if (r < 2 * I_W2) {
;             const bool second = r >= I_W2; if (second) r -= I_W2;
;             const float* W = a.in[second ? 15 : 3] + (size_t)l * DFF * D;
;             const int nblk = D / 32, kb = r / nblk, nb = r % nblk;
;             tr_item(W, DFF, D, nullptr, (bf16*)(wl + (second ? W4_OFF : W2_OFF)), 32 * nb, scr, 64 * kb, 32 * nb, lane);
;             continue;
;         }
;         r -= 2 * I_W2;
;         if (r < I_WIN) {
;             const float* W = a.in[5] + (size_t)l * D * INCOLS; const float* ks = a.in[4] + (size_t)l * D;
;             const int nblk = NPROJ / 32, kb = r / nblk, nb = r % nblk;
;             tr_item(W, D, INCOLS, ks, (bf16*)(wl + WIN_OFF), 32 * nb, scr, 64 * kb, 32 * nb, lane);
.Lwq_nm_1:
	v_add_u32_e32 v15, s30, v14
	v_add_u32_e32 v16, s30, v15
	v_add_u32_e32 v17, s30, v16
	v_add_u32_e32 v18, s30, v17
	v_add_u32_e32 v19, s30, v18
	v_add_u32_e32 v20, s30, v19
	v_add_u32_e32 v21, s30, v20
	global_load_dwordx4 v[120:123], v14, s[74:75] nt
	global_load_dwordx4 v[124:127], v15, s[74:75] nt
	global_load_dwordx4 v[128:131], v16, s[74:75] nt
	global_load_dwordx4 v[132:135], v17, s[74:75] nt
	global_load_dwordx4 v[136:139], v18, s[74:75] nt
	global_load_dwordx4 v[140:143], v19, s[74:75] nt
	global_load_dwordx4 v[144:147], v20, s[74:75] nt
	global_load_dwordx4 v[148:151], v21, s[74:75] nt
	global_load_dwordx4 v[152:155], v4, s[76:77]
	global_load_dwordx4 v[156:159], v4, s[76:77] offset:16
	s_waitcnt vmcnt(10)
	s_branch .Lwq_proc0

; __device__ __forceinline__ void tr_item(const float* W, int K, int N, const float* kscale, bf16* WT, int dst_row0, LAS float* scr, int k0, int n0, int lane) {
;     const int n4 = 4 * (lane & 7); const bool ok = (n0 + n4) < N;
; #pragma unroll
;     for (int i = 0; i < 8; ++i) { const int kk = 8 * i + (lane >> 3); f32x4 v = ok ? *(const f32x4*)(W + (size_t)(k0 + kk) * N + n0 + n4) : (f32x4){0.f, 0.f, 0.f, 0.f}; if (kscale) v = v * kscale[k0 + kk];
; __device__ __forceinline__ void prologue(const Args& a, LAS unsigned char* lds, int wave, int lane) {
;     ...
;     for (int it = gw; it < DEPTH * I_L; it += NGW) {
;         const int l = it / I_L; int r = it % I_L;
;         unsigned char* wl = ws + WS_W + (size_t)l * W_L;
;         if (r < 2 * I_W1) {
;             const bool second = r >= I_W1; if (second) r -= I_W1;
;             const float* W = a.in[second ? 14 : 2] + (size_t)l * D * NFF; const float* ks = a.in[second ? 13 : 1] + (size_t)l * D;
;             const int nblk = NFF / 32, kb = r / nblk, nb = r % nblk, n0 = 32 * nb;
;             const int dst = n0 < DFF ? (n0 / 128) * 256 + (n0 % 128) : ((n0 - DFF) / 128) * 256 + 128 + ((n0 - DFF) % 128);
;             tr_item(W, D, NFF, ks, (bf16*)(wl + (second ? W3_OFF : W1_OFF)), dst, scr, 64 * kb, n0, lane);
;             continue;
;         }
;         r -= 2 * I_W1;
;         if (r < 2 * I_W2) {
;             const bool second = r >= I_W2; if (second) r -= I_W2;
;             const float* W = a.in[second ? 15 : 3] + (size_t)l * DFF * D;
;             const int nblk = D / 32, kb = r / nblk, nb = r % nblk;
;             tr_item(W, DFF, D, nullptr, (bf16*)(wl + (second ? W4_OFF : W2_OFF)), 32 * nb, scr, 64 * kb, 32 * nb, lane);
;             continue;
;         }
;         r -= 2 * I_W2;
;         if (r < I_WIN) {
;             const float* W = a.in[5] + (size_t)l * D * INCOLS; const float* ks = a.in[4] + (size_t)l * D;
;             const int nblk = NPROJ / 32, kb = r / nblk, nb = r % nblk;
;             tr_item(W, D, INCOLS, ks, (bf16*)(wl + WIN_OFF), 32 * nb, scr, 64 * kb, 32 * nb, lane);
.Lwq_nm_3:
	v_add_u32_e32 v15, s30, v14
	v_add_u32_e32 v16, s30, v15
	v_add_u32_e32 v17, s30, v16
	v_add_u32_e32 v18, s30, v17
	v_add_u32_e32 v19, s30, v18
	v_add_u32_e32 v20, s30, v19
	v_add_u32_e32 v21, s30, v20
	global_load_dwordx4 v[80:83], v14, s[64:65] nt
	global_load_dwordx4 v[84:87], v15, s[64:65] nt
	global_load_dwordx4 v[88:91], v16, s[64:65] nt
	global_load_dwordx4 v[92:95], v17, s[64:65] nt
	global_load_dwordx4 v[96:99], v18, s[64:65] nt
	global_load_dwordx4 v[100:103], v19, s[64:65] nt
	global_load_dwordx4 v[104:107], v20, s[64:65] nt
	global_load_dwordx4 v[108:111], v21, s[64:65] nt
	global_load_dwordx4 v[112:115], v4, s[66:67]
	global_load_dwordx4 v[116:119], v4, s[66:67] offset:16
	s_waitcnt vmcnt(10)
	s_branch .Lwq_proc1
